# add: P5 out-proj epilogue issues the four residual loads of a row group together (8 HBM round trips per tile instead of 16)
# baseline (speedup 1.0000x reference)
.LBB0_976:
	s_or_b64 exec, exec, s[26:27]
	v_lshl_or_b32 v154, s24, 8, v168
	v_ashrrev_i32_e32 v159, 31, v158
	v_ashrrev_i32_e32 v155, 31, v154
	v_lshlrev_b64 v[128:129], 13, v[158:159]
	v_cmp_ne_u64_e32 vcc, 0, v[162:163]
	v_lshlrev_b64 v[156:157], 2, v[154:155]
	v_lshl_add_u64 v[160:161], s[8:9], 0, v[128:129]
	s_and_saveexec_b64 s[24:25], vcc
	s_xor_b64 s[24:25], exec, s[24:25]
	s_cbranch_execz .LBB0_978
	v_lshl_add_u64 v[162:163], v[162:163], 0, v[156:157]
	global_load_dwordx4 v[128:131], v[162:163], off nt
	global_load_dwordx4 v[132:135], v[162:163], off offset:16 nt
	global_load_dwordx4 v[180:183], v[162:163], off offset:512 nt
	global_load_dwordx4 v[184:187], v[162:163], off offset:528 nt
	v_lshl_add_u64 v[172:173], v[160:161], 0, v[156:157]
	s_waitcnt vmcnt(2)
	v_pk_add_f32 v[130:131], v[126:127], v[130:131]
	v_pk_add_f32 v[128:129], v[124:125], v[128:129]
	v_pk_add_f32 v[134:135], v[122:123], v[134:135]
	v_pk_add_f32 v[132:133], v[120:121], v[132:133]
	global_store_dwordx4 v[172:173], v[128:131], off
	global_store_dwordx4 v[172:173], v[132:135], off offset:16
	s_nop 0
	s_nop 0
	s_nop 0
	s_waitcnt vmcnt(3)
	v_pk_add_f32 v[130:131], v[118:119], v[182:183]
	v_pk_add_f32 v[128:129], v[116:117], v[180:181]
	s_waitcnt vmcnt(2)
	v_pk_add_f32 v[134:135], v[114:115], v[186:187]
	v_pk_add_f32 v[132:133], v[112:113], v[184:185]

.LBB0_988:
	s_or_b64 exec, exec, s[24:25]
	v_ashrrev_i32_e32 v113, 31, v112
	v_lshlrev_b64 v[112:113], 13, v[112:113]
	v_cmp_ne_u64_e32 vcc, 0, v[122:123]
	v_lshl_add_u64 v[120:121], s[8:9], 0, v[112:113]
	s_and_saveexec_b64 s[24:25], vcc
	s_xor_b64 s[24:25], exec, s[24:25]
	s_cbranch_execz .LBB0_990
	v_lshl_add_u64 v[122:123], v[122:123], 0, v[156:157]
	global_load_dwordx4 v[112:115], v[122:123], off nt
	global_load_dwordx4 v[116:119], v[122:123], off offset:16 nt
	global_load_dwordx4 v[180:183], v[122:123], off offset:512 nt
	global_load_dwordx4 v[184:187], v[122:123], off offset:528 nt
	v_lshl_add_u64 v[124:125], v[120:121], 0, v[156:157]
	s_waitcnt vmcnt(2)
	v_pk_add_f32 v[114:115], v[110:111], v[114:115]
	v_pk_add_f32 v[112:113], v[108:109], v[112:113]
	v_pk_add_f32 v[118:119], v[106:107], v[118:119]
	v_pk_add_f32 v[116:117], v[104:105], v[116:117]
	global_store_dwordx4 v[124:125], v[112:115], off
	global_store_dwordx4 v[124:125], v[116:119], off offset:16
	s_nop 0
	s_nop 0
	s_nop 0
	s_waitcnt vmcnt(3)
	v_pk_add_f32 v[114:115], v[102:103], v[182:183]
	v_pk_add_f32 v[112:113], v[100:101], v[180:181]
	s_waitcnt vmcnt(2)
	v_pk_add_f32 v[118:119], v[98:99], v[186:187]
	v_pk_add_f32 v[116:117], v[96:97], v[184:185]

.LBB0_1000:
	s_or_b64 exec, exec, s[24:25]
	v_ashrrev_i32_e32 v97, 31, v96
	v_lshlrev_b64 v[96:97], 13, v[96:97]
	v_cmp_ne_u64_e32 vcc, 0, v[106:107]
	v_lshl_add_u64 v[104:105], s[8:9], 0, v[96:97]
	s_and_saveexec_b64 s[24:25], vcc
	s_xor_b64 s[24:25], exec, s[24:25]
	s_cbranch_execz .LBB0_1002
	v_lshl_add_u64 v[106:107], v[106:107], 0, v[156:157]
	global_load_dwordx4 v[96:99], v[106:107], off nt
	global_load_dwordx4 v[100:103], v[106:107], off offset:16 nt
	global_load_dwordx4 v[180:183], v[106:107], off offset:512 nt
	global_load_dwordx4 v[184:187], v[106:107], off offset:528 nt
	v_lshl_add_u64 v[108:109], v[104:105], 0, v[156:157]
	s_waitcnt vmcnt(2)
	v_pk_add_f32 v[98:99], v[94:95], v[98:99]
	v_pk_add_f32 v[96:97], v[92:93], v[96:97]
	v_pk_add_f32 v[102:103], v[90:91], v[102:103]
	v_pk_add_f32 v[100:101], v[88:89], v[100:101]
	global_store_dwordx4 v[108:109], v[96:99], off
	global_store_dwordx4 v[108:109], v[100:103], off offset:16
	s_nop 0
	s_nop 0
	s_nop 0
	s_waitcnt vmcnt(3)
	v_pk_add_f32 v[98:99], v[86:87], v[182:183]
	v_pk_add_f32 v[96:97], v[84:85], v[180:181]
	s_waitcnt vmcnt(2)
	v_pk_add_f32 v[102:103], v[82:83], v[186:187]
	v_pk_add_f32 v[100:101], v[80:81], v[184:185]

.LBB0_1012:
	s_or_b64 exec, exec, s[24:25]
	v_ashrrev_i32_e32 v81, 31, v80
	v_lshlrev_b64 v[80:81], 13, v[80:81]
	v_cmp_ne_u64_e32 vcc, 0, v[90:91]
	v_lshl_add_u64 v[88:89], s[8:9], 0, v[80:81]
	s_and_saveexec_b64 s[2:3], vcc
	s_xor_b64 s[24:25], exec, s[2:3]
	s_cbranch_execz .LBB0_1014
	v_lshl_add_u64 v[90:91], v[90:91], 0, v[156:157]
	global_load_dwordx4 v[80:83], v[90:91], off nt
	global_load_dwordx4 v[84:87], v[90:91], off offset:16 nt
	global_load_dwordx4 v[180:183], v[90:91], off offset:512 nt
	global_load_dwordx4 v[184:187], v[90:91], off offset:528 nt
	v_lshl_add_u64 v[92:93], v[88:89], 0, v[156:157]
	s_waitcnt vmcnt(2)
	v_pk_add_f32 v[82:83], v[78:79], v[82:83]
	v_pk_add_f32 v[80:81], v[76:77], v[80:81]
	v_pk_add_f32 v[86:87], v[74:75], v[86:87]
	v_pk_add_f32 v[84:85], v[72:73], v[84:85]
	global_store_dwordx4 v[92:93], v[80:83], off
	global_store_dwordx4 v[92:93], v[84:87], off offset:16
	s_nop 0
	s_nop 0
	s_nop 0
	s_waitcnt vmcnt(3)
	v_pk_add_f32 v[82:83], v[70:71], v[182:183]
	v_pk_add_f32 v[80:81], v[68:69], v[180:181]
	s_waitcnt vmcnt(2)
	v_pk_add_f32 v[86:87], v[66:67], v[186:187]
	v_pk_add_f32 v[84:85], v[64:65], v[184:185]

.LBB0_1024:
	s_or_b64 exec, exec, s[24:25]
	v_ashrrev_i32_e32 v65, 31, v64
	v_lshlrev_b64 v[64:65], 13, v[64:65]
	v_cmp_ne_u64_e32 vcc, 0, v[74:75]
	v_lshl_add_u64 v[72:73], s[8:9], 0, v[64:65]
	s_and_saveexec_b64 s[2:3], vcc
	s_xor_b64 s[24:25], exec, s[2:3]
	s_cbranch_execz .LBB0_1026
	v_lshl_add_u64 v[74:75], v[74:75], 0, v[156:157]
	global_load_dwordx4 v[64:67], v[74:75], off nt
	global_load_dwordx4 v[68:71], v[74:75], off offset:16 nt
	global_load_dwordx4 v[180:183], v[74:75], off offset:512 nt
	global_load_dwordx4 v[184:187], v[74:75], off offset:528 nt
	v_lshl_add_u64 v[76:77], v[72:73], 0, v[156:157]
	s_waitcnt vmcnt(2)
	v_pk_add_f32 v[66:67], v[62:63], v[66:67]
	v_pk_add_f32 v[64:65], v[60:61], v[64:65]
	v_pk_add_f32 v[70:71], v[58:59], v[70:71]
	v_pk_add_f32 v[68:69], v[56:57], v[68:69]
	global_store_dwordx4 v[76:77], v[64:67], off
	global_store_dwordx4 v[76:77], v[68:71], off offset:16
	s_nop 0
	s_nop 0
	s_nop 0
	s_waitcnt vmcnt(3)
	v_pk_add_f32 v[66:67], v[54:55], v[182:183]
	v_pk_add_f32 v[64:65], v[52:53], v[180:181]
	s_waitcnt vmcnt(2)
	v_pk_add_f32 v[70:71], v[50:51], v[186:187]
	v_pk_add_f32 v[68:69], v[48:49], v[184:185]

.LBB0_1036:
	s_or_b64 exec, exec, s[24:25]
	v_ashrrev_i32_e32 v49, 31, v48
	v_lshlrev_b64 v[48:49], 13, v[48:49]
	v_cmp_ne_u64_e32 vcc, 0, v[58:59]
	v_lshl_add_u64 v[56:57], s[8:9], 0, v[48:49]
	s_and_saveexec_b64 s[2:3], vcc
	s_xor_b64 s[24:25], exec, s[2:3]
	s_cbranch_execz .LBB0_1038
	v_lshl_add_u64 v[58:59], v[58:59], 0, v[156:157]
	global_load_dwordx4 v[48:51], v[58:59], off nt
	global_load_dwordx4 v[52:55], v[58:59], off offset:16 nt
	global_load_dwordx4 v[180:183], v[58:59], off offset:512 nt
	global_load_dwordx4 v[184:187], v[58:59], off offset:528 nt
	v_lshl_add_u64 v[60:61], v[56:57], 0, v[156:157]
	s_waitcnt vmcnt(2)
	v_pk_add_f32 v[50:51], v[46:47], v[50:51]
	v_pk_add_f32 v[48:49], v[44:45], v[48:49]
	v_pk_add_f32 v[54:55], v[42:43], v[54:55]
	v_pk_add_f32 v[52:53], v[40:41], v[52:53]
	global_store_dwordx4 v[60:61], v[48:51], off
	global_store_dwordx4 v[60:61], v[52:55], off offset:16
	s_nop 0
	s_nop 0
	s_nop 0
	s_waitcnt vmcnt(3)
	v_pk_add_f32 v[50:51], v[38:39], v[182:183]
	v_pk_add_f32 v[48:49], v[36:37], v[180:181]
	s_waitcnt vmcnt(2)
	v_pk_add_f32 v[54:55], v[34:35], v[186:187]
	v_pk_add_f32 v[52:53], v[32:33], v[184:185]

.LBB0_1048:
	s_or_b64 exec, exec, s[24:25]
	v_ashrrev_i32_e32 v33, 31, v32
	v_lshlrev_b64 v[32:33], 13, v[32:33]
	v_cmp_ne_u64_e32 vcc, 0, v[42:43]
	v_lshl_add_u64 v[40:41], s[8:9], 0, v[32:33]
	s_and_saveexec_b64 s[2:3], vcc
	s_xor_b64 s[24:25], exec, s[2:3]
	s_cbranch_execz .LBB0_1050
	v_lshl_add_u64 v[42:43], v[42:43], 0, v[156:157]
	global_load_dwordx4 v[32:35], v[42:43], off nt
	global_load_dwordx4 v[36:39], v[42:43], off offset:16 nt
	global_load_dwordx4 v[180:183], v[42:43], off offset:512 nt
	global_load_dwordx4 v[184:187], v[42:43], off offset:528 nt
	v_lshl_add_u64 v[44:45], v[40:41], 0, v[156:157]
	s_waitcnt vmcnt(2)
	v_pk_add_f32 v[34:35], v[30:31], v[34:35]
	v_pk_add_f32 v[32:33], v[28:29], v[32:33]
	v_pk_add_f32 v[38:39], v[26:27], v[38:39]
	v_pk_add_f32 v[36:37], v[24:25], v[36:37]
	global_store_dwordx4 v[44:45], v[32:35], off
	global_store_dwordx4 v[44:45], v[36:39], off offset:16
	s_nop 0
	s_nop 0
	s_nop 0
	s_waitcnt vmcnt(3)
	v_pk_add_f32 v[34:35], v[22:23], v[182:183]
	v_pk_add_f32 v[32:33], v[20:21], v[180:181]
	s_waitcnt vmcnt(2)
	v_pk_add_f32 v[38:39], v[18:19], v[186:187]
	v_pk_add_f32 v[36:37], v[16:17], v[184:185]

.LBB0_1060:
	s_or_b64 exec, exec, s[24:25]
	v_ashrrev_i32_e32 v17, 31, v16
	v_lshlrev_b64 v[16:17], 13, v[16:17]
	v_cmp_ne_u64_e32 vcc, 0, v[26:27]
	v_lshl_add_u64 v[24:25], s[8:9], 0, v[16:17]
	s_and_saveexec_b64 s[2:3], vcc
	s_xor_b64 s[24:25], exec, s[2:3]
	s_cbranch_execz .LBB0_1062
	v_lshl_add_u64 v[26:27], v[26:27], 0, v[156:157]
	global_load_dwordx4 v[16:19], v[26:27], off nt
	global_load_dwordx4 v[20:23], v[26:27], off offset:16 nt
	global_load_dwordx4 v[180:183], v[26:27], off offset:512 nt
	global_load_dwordx4 v[184:187], v[26:27], off offset:528 nt
	v_lshl_add_u64 v[28:29], v[24:25], 0, v[156:157]
	s_waitcnt vmcnt(2)
	v_pk_add_f32 v[18:19], v[14:15], v[18:19]
	v_pk_add_f32 v[16:17], v[12:13], v[16:17]
	v_pk_add_f32 v[22:23], v[10:11], v[22:23]
	v_pk_add_f32 v[20:21], v[8:9], v[20:21]
	global_store_dwordx4 v[28:29], v[16:19], off
	global_store_dwordx4 v[28:29], v[20:23], off offset:16
	s_nop 0
	s_nop 0
	s_nop 0
	s_waitcnt vmcnt(3)
	v_pk_add_f32 v[18:19], v[6:7], v[182:183]
	v_pk_add_f32 v[16:17], v[4:5], v[180:181]
	s_waitcnt vmcnt(2)
	v_pk_add_f32 v[22:23], v[2:3], v[186:187]
	v_pk_add_f32 v[20:21], v[0:1], v[184:185]
